# P0 w_in conversion rewritten with the seam routine: each wave issues all three tiles' loads (dwordx4) up front, then transposes/scales/stores
# speedup vs baseline: 1.0106x; 1.0064x over previous
.LBB0_21:
	s_lshr_b32 s95, s56, 6
	s_add_u32 s56, s26, 0x200000
	s_addc_u32 s57, s27, 0
	s_add_u32 s6, s26, 0x1a00000
	s_addc_u32 s7, s27, 0
	s_add_u32 s52, s26, 0x2200000
	s_addc_u32 s53, s27, 0
	s_add_u32 s58, s26, 0x100000
	s_addc_u32 s59, s27, 0
	s_cmp_lt_i32 s28, 1
	s_cselect_b64 s[0:1], -1, 0
	s_cmp_gt_i32 s29, 0
	s_cselect_b64 s[4:5], -1, 0
	s_and_b64 s[60:61], s[0:1], s[4:5]
	s_andn2_b64 vcc, exec, s[60:61]
	v_and_b32_e32 v209, 63, v208
	s_cbranch_vccnz .LBB0_253
	s_lshl_b32 s0, s3, 3
	s_add_i32 s62, s0, s95
	s_lshl_b32 s64, s30, 3
	s_cmpk_gt_i32 s62, 0x17ff
	s_cbranch_scc1 .LBB0_241
	s_cmpk_lg_u32 s64, 0x800
	s_cbranch_scc1 .Lmy_p0_skip
	s_lshl_b32 s72, s95, 14
	v_and_b32_e32 v8, 7, v209
	v_lshrrev_b32_e32 v9, 3, v209
	v_mul_u32_u24_e32 v0, 0x6000, v9
	v_lshl_add_u32 v0, v8, 4, v0
	v_mul_u32_u24_e32 v2, 0x420, v8
	v_lshl_add_u32 v2, v9, 2, v2
	v_add_u32_e32 v2, s72, v2
	v_mul_u32_u24_e32 v3, 0x108, v9
	v_lshl_add_u32 v3, v8, 5, v3
	v_add_u32_e32 v3, s72, v3
	v_lshlrev_b32_e32 v4, 12, v9
	v_lshl_add_u32 v4, v8, 4, v4
	v_lshlrev_b32_e32 v5, 5, v8
	s_waitcnt lgkmcnt(0)
	s_add_i32 s0, s62, 0x0
	s_mul_hi_u32 s65, s0, 0x1555556
	s_mul_i32 s1, s65, 0xc0
	s_sub_u32 s66, s0, s1
	s_mul_i32 s70, s65, 0x180000
	s_lshl_b32 s71, s66, 7
	s_add_u32 s68, s40, s70
	s_addc_u32 s69, s41, 0
	s_add_u32 s68, s68, s71
	s_addc_u32 s69, s69, 0
	v_mov_b32_e32 v1, v0
	global_load_dwordx4 v[112:115], v1, s[68:69] nt
	v_add_u32_e32 v1, 0x30000, v1
	global_load_dwordx4 v[116:119], v1, s[68:69] nt
	v_add_u32_e32 v1, 0x30000, v1
	global_load_dwordx4 v[120:123], v1, s[68:69] nt
	v_add_u32_e32 v1, 0x30000, v1
	global_load_dwordx4 v[124:127], v1, s[68:69] nt
	v_add_u32_e32 v1, 0x30000, v1
	global_load_dwordx4 v[128:131], v1, s[68:69] nt
	v_add_u32_e32 v1, 0x30000, v1
	global_load_dwordx4 v[132:135], v1, s[68:69] nt
	v_add_u32_e32 v1, 0x30000, v1
	global_load_dwordx4 v[136:139], v1, s[68:69] nt
	v_add_u32_e32 v1, 0x30000, v1
	global_load_dwordx4 v[140:143], v1, s[68:69] nt
	s_lshl_b32 s70, s65, 8
	s_add_u32 s70, s38, s70
	s_addc_u32 s71, s39, 0
	global_load_dwordx4 v[144:147], v5, s[70:71]
	global_load_dwordx4 v[148:151], v5, s[70:71] offset:16
	s_add_i32 s0, s62, 0x800
	s_mul_hi_u32 s67, s0, 0x1555556
	s_mul_i32 s1, s67, 0xc0
	s_sub_u32 s73, s0, s1
	s_mul_i32 s70, s67, 0x180000
	s_lshl_b32 s71, s73, 7
	s_add_u32 s68, s40, s70
	s_addc_u32 s69, s41, 0
	s_add_u32 s68, s68, s71
	s_addc_u32 s69, s69, 0
	v_mov_b32_e32 v1, v0
	global_load_dwordx4 v[32:35], v1, s[68:69] nt
	v_add_u32_e32 v1, 0x30000, v1
	global_load_dwordx4 v[36:39], v1, s[68:69] nt
	v_add_u32_e32 v1, 0x30000, v1
	global_load_dwordx4 v[40:43], v1, s[68:69] nt
	v_add_u32_e32 v1, 0x30000, v1
	global_load_dwordx4 v[44:47], v1, s[68:69] nt
	v_add_u32_e32 v1, 0x30000, v1
	global_load_dwordx4 v[48:51], v1, s[68:69] nt
	v_add_u32_e32 v1, 0x30000, v1
	global_load_dwordx4 v[52:55], v1, s[68:69] nt
	v_add_u32_e32 v1, 0x30000, v1
	global_load_dwordx4 v[56:59], v1, s[68:69] nt
	v_add_u32_e32 v1, 0x30000, v1
	global_load_dwordx4 v[60:63], v1, s[68:69] nt
	s_lshl_b32 s70, s67, 8
	s_add_u32 s70, s38, s70
	s_addc_u32 s71, s39, 0
	global_load_dwordx4 v[96:99], v5, s[70:71]
	global_load_dwordx4 v[100:103], v5, s[70:71] offset:16
	s_add_i32 s0, s62, 0x1000
	s_mul_hi_u32 s74, s0, 0x1555556
	s_mul_i32 s1, s74, 0xc0
	s_sub_u32 s75, s0, s1
	s_mul_i32 s70, s74, 0x180000
	s_lshl_b32 s71, s75, 7
	s_add_u32 s68, s40, s70
	s_addc_u32 s69, s41, 0
	s_add_u32 s68, s68, s71
	s_addc_u32 s69, s69, 0
	v_mov_b32_e32 v1, v0
	global_load_dwordx4 v[64:67], v1, s[68:69] nt
	v_add_u32_e32 v1, 0x30000, v1
	global_load_dwordx4 v[68:71], v1, s[68:69] nt
	v_add_u32_e32 v1, 0x30000, v1
	global_load_dwordx4 v[72:75], v1, s[68:69] nt
	v_add_u32_e32 v1, 0x30000, v1
	global_load_dwordx4 v[76:79], v1, s[68:69] nt
	v_add_u32_e32 v1, 0x30000, v1
	global_load_dwordx4 v[80:83], v1, s[68:69] nt
	v_add_u32_e32 v1, 0x30000, v1
	global_load_dwordx4 v[84:87], v1, s[68:69] nt
	v_add_u32_e32 v1, 0x30000, v1
	global_load_dwordx4 v[88:91], v1, s[68:69] nt
	v_add_u32_e32 v1, 0x30000, v1
	global_load_dwordx4 v[92:95], v1, s[68:69] nt
	s_lshl_b32 s70, s74, 8
	s_add_u32 s70, s38, s70
	s_addc_u32 s71, s39, 0
	global_load_dwordx4 v[104:107], v5, s[70:71]
	global_load_dwordx4 v[108:111], v5, s[70:71] offset:16
	s_waitcnt vmcnt(20)
	s_waitcnt lgkmcnt(0)
	ds_write_b32 v2, v112 offset:0
	ds_write_b32 v2, v113 offset:264
	ds_write_b32 v2, v114 offset:528
	ds_write_b32 v2, v115 offset:792
	ds_write_b32 v2, v116 offset:32
	ds_write_b32 v2, v117 offset:296
	ds_write_b32 v2, v118 offset:560
	ds_write_b32 v2, v119 offset:824
	ds_write_b32 v2, v120 offset:64
	ds_write_b32 v2, v121 offset:328
	ds_write_b32 v2, v122 offset:592
	ds_write_b32 v2, v123 offset:856
	ds_write_b32 v2, v124 offset:96
	ds_write_b32 v2, v125 offset:360
	ds_write_b32 v2, v126 offset:624
	ds_write_b32 v2, v127 offset:888
	ds_write_b32 v2, v128 offset:128
	ds_write_b32 v2, v129 offset:392
	ds_write_b32 v2, v130 offset:656
	ds_write_b32 v2, v131 offset:920
	ds_write_b32 v2, v132 offset:160
	ds_write_b32 v2, v133 offset:424
	ds_write_b32 v2, v134 offset:688
	ds_write_b32 v2, v135 offset:952
	ds_write_b32 v2, v136 offset:192
	ds_write_b32 v2, v137 offset:456
	ds_write_b32 v2, v138 offset:720
	ds_write_b32 v2, v139 offset:984
	ds_write_b32 v2, v140 offset:224
	ds_write_b32 v2, v141 offset:488
	ds_write_b32 v2, v142 offset:752
	ds_write_b32 v2, v143 offset:1016
	s_lshr_b32 s77, s66, 5
	s_and_b32 s78, s66, 31
	s_cmp_lt_u32 s77, 2
	s_cbranch_scc0 .Lmy_p0_i0_nqk
	s_and_b32 s79, s78, 1
	s_lshl_b32 s79, s79, 7
	s_bfe_u32 s80, s78, 0x20001
	s_lshl_b32 s80, s80, 5
	s_add_i32 s79, s79, s80
	s_lshr_b32 s76, s78, 3
	s_cmp_eq_u32 s77, 1
	s_cselect_b32 s80, 12, 0
	s_add_i32 s76, s76, s80
	s_lshl_b32 s76, s76, 8
	s_add_i32 s76, s76, s79
	s_branch .Lmy_p0_i0_dd
.Lmy_p0_i0_nqk:
	s_cmp_lt_u32 s77, 4
	s_cbranch_scc0 .Lmy_p0_i0_gc
	s_lshl_b32 s76, s78, 5
	s_cmp_eq_u32 s77, 2
	s_movk_i32 s80, 0x1000
	s_cselect_b32 s80, 0x400, s80
	s_add_i32 s76, s76, s80
	s_branch .Lmy_p0_i0_dd
.Lmy_p0_i0_gc:
	s_lshr_b32 s79, s78, 2
	s_cmp_lt_u32 s79, 4
	s_cselect_b32 s80, 8, 16
	s_add_i32 s79, s79, s80
	s_lshl_b32 s76, s79, 8
	s_and_b32 s79, s78, 3
	s_lshl_b32 s79, s79, 5
	s_add_i32 s76, s76, s79
	s_cmp_eq_u32 s77, 5
	s_cselect_b32 s80, 128, 0
	s_add_i32 s76, s76, s80
.Lmy_p0_i0_dd:
	s_lshl_b32 s70, s76, 12
	s_lshl_b32 s71, s65, 7
	s_add_i32 s70, s70, s71
	s_add_u32 s70, s70, 0x200000
	s_add_u32 s70, s26, s70
	s_addc_u32 s71, s27, 0
	s_waitcnt lgkmcnt(0)
	ds_read_b64 v[160:161], v3 offset:0
	ds_read_b64 v[162:163], v3 offset:8
	ds_read_b64 v[164:165], v3 offset:16
	ds_read_b64 v[166:167], v3 offset:24
	ds_read_b64 v[168:169], v3 offset:2112
	ds_read_b64 v[170:171], v3 offset:2120
	ds_read_b64 v[172:173], v3 offset:2128
	ds_read_b64 v[174:175], v3 offset:2136
	ds_read_b64 v[176:177], v3 offset:4224
	ds_read_b64 v[178:179], v3 offset:4232
	ds_read_b64 v[180:181], v3 offset:4240
	ds_read_b64 v[182:183], v3 offset:4248
	ds_read_b64 v[184:185], v3 offset:6336
	ds_read_b64 v[186:187], v3 offset:6344
	ds_read_b64 v[188:189], v3 offset:6352
	ds_read_b64 v[190:191], v3 offset:6360
	s_waitcnt lgkmcnt(12)
	v_mul_f32_e32 v160, v160, v144
	v_mul_f32_e32 v161, v161, v145
	v_mul_f32_e32 v162, v162, v146
	v_mul_f32_e32 v163, v163, v147
	v_mul_f32_e32 v164, v164, v148
	v_mul_f32_e32 v165, v165, v149
	v_mul_f32_e32 v166, v166, v150
	v_mul_f32_e32 v167, v167, v151
	v_cvt_pk_bf16_f32 v192, v160, v161
	v_cvt_pk_bf16_f32 v193, v162, v163
	v_cvt_pk_bf16_f32 v194, v164, v165
	v_cvt_pk_bf16_f32 v195, v166, v167
	v_mov_b32_e32 v9, v4
	global_store_dwordx4 v9, v[192:195], s[70:71]
	s_waitcnt lgkmcnt(8)
	v_mul_f32_e32 v168, v168, v144
	v_mul_f32_e32 v169, v169, v145
	v_mul_f32_e32 v170, v170, v146
	v_mul_f32_e32 v171, v171, v147
	v_mul_f32_e32 v172, v172, v148
	v_mul_f32_e32 v173, v173, v149
	v_mul_f32_e32 v174, v174, v150
	v_mul_f32_e32 v175, v175, v151
	v_cvt_pk_bf16_f32 v196, v168, v169
	v_cvt_pk_bf16_f32 v197, v170, v171
	v_cvt_pk_bf16_f32 v198, v172, v173
	v_cvt_pk_bf16_f32 v199, v174, v175
	v_add_u32_e32 v9, 0x8000, v9
	global_store_dwordx4 v9, v[196:199], s[70:71]
	s_waitcnt lgkmcnt(4)
	v_mul_f32_e32 v176, v176, v144
	v_mul_f32_e32 v177, v177, v145
	v_mul_f32_e32 v178, v178, v146
	v_mul_f32_e32 v179, v179, v147
	v_mul_f32_e32 v180, v180, v148
	v_mul_f32_e32 v181, v181, v149
	v_mul_f32_e32 v182, v182, v150
	v_mul_f32_e32 v183, v183, v151
	v_cvt_pk_bf16_f32 v200, v176, v177
	v_cvt_pk_bf16_f32 v201, v178, v179
	v_cvt_pk_bf16_f32 v202, v180, v181
	v_cvt_pk_bf16_f32 v203, v182, v183
	v_add_u32_e32 v9, 0x8000, v9
	global_store_dwordx4 v9, v[200:203], s[70:71]
	s_waitcnt lgkmcnt(0)
	v_mul_f32_e32 v184, v184, v144
	v_mul_f32_e32 v185, v185, v145
	v_mul_f32_e32 v186, v186, v146
	v_mul_f32_e32 v187, v187, v147
	v_mul_f32_e32 v188, v188, v148
	v_mul_f32_e32 v189, v189, v149
	v_mul_f32_e32 v190, v190, v150
	v_mul_f32_e32 v191, v191, v151
	v_cvt_pk_bf16_f32 v204, v184, v185
	v_cvt_pk_bf16_f32 v205, v186, v187
	v_cvt_pk_bf16_f32 v206, v188, v189
	v_cvt_pk_bf16_f32 v207, v190, v191
	v_add_u32_e32 v9, 0x8000, v9
	global_store_dwordx4 v9, v[204:207], s[70:71]
	s_waitcnt vmcnt(10)
	s_waitcnt lgkmcnt(0)
	ds_write_b32 v2, v32 offset:0
	ds_write_b32 v2, v33 offset:264
	ds_write_b32 v2, v34 offset:528
	ds_write_b32 v2, v35 offset:792
	ds_write_b32 v2, v36 offset:32
	ds_write_b32 v2, v37 offset:296
	ds_write_b32 v2, v38 offset:560
	ds_write_b32 v2, v39 offset:824
	ds_write_b32 v2, v40 offset:64
	ds_write_b32 v2, v41 offset:328
	ds_write_b32 v2, v42 offset:592
	ds_write_b32 v2, v43 offset:856
	ds_write_b32 v2, v44 offset:96
	ds_write_b32 v2, v45 offset:360
	ds_write_b32 v2, v46 offset:624
	ds_write_b32 v2, v47 offset:888
	ds_write_b32 v2, v48 offset:128
	ds_write_b32 v2, v49 offset:392
	ds_write_b32 v2, v50 offset:656
	ds_write_b32 v2, v51 offset:920
	ds_write_b32 v2, v52 offset:160
	ds_write_b32 v2, v53 offset:424
	ds_write_b32 v2, v54 offset:688
	ds_write_b32 v2, v55 offset:952
	ds_write_b32 v2, v56 offset:192
	ds_write_b32 v2, v57 offset:456
	ds_write_b32 v2, v58 offset:720
	ds_write_b32 v2, v59 offset:984
	ds_write_b32 v2, v60 offset:224
	ds_write_b32 v2, v61 offset:488
	ds_write_b32 v2, v62 offset:752
	ds_write_b32 v2, v63 offset:1016
	s_lshr_b32 s77, s73, 5
	s_and_b32 s78, s73, 31
	s_cmp_lt_u32 s77, 2
	s_cbranch_scc0 .Lmy_p0_i1_nqk
	s_and_b32 s79, s78, 1
	s_lshl_b32 s79, s79, 7
	s_bfe_u32 s80, s78, 0x20001
	s_lshl_b32 s80, s80, 5
	s_add_i32 s79, s79, s80
	s_lshr_b32 s76, s78, 3
	s_cmp_eq_u32 s77, 1
	s_cselect_b32 s80, 12, 0
	s_add_i32 s76, s76, s80
	s_lshl_b32 s76, s76, 8
	s_add_i32 s76, s76, s79
	s_branch .Lmy_p0_i1_dd

.Lmy_p0_i1_dd:
	s_lshl_b32 s70, s76, 12
	s_lshl_b32 s71, s67, 7
	s_add_i32 s70, s70, s71
	s_add_u32 s70, s70, 0x200000
	s_add_u32 s70, s26, s70
	s_addc_u32 s71, s27, 0
	s_waitcnt lgkmcnt(0)
	ds_read_b64 v[160:161], v3 offset:0
	ds_read_b64 v[162:163], v3 offset:8
	ds_read_b64 v[164:165], v3 offset:16
	ds_read_b64 v[166:167], v3 offset:24
	ds_read_b64 v[168:169], v3 offset:2112
	ds_read_b64 v[170:171], v3 offset:2120
	ds_read_b64 v[172:173], v3 offset:2128
	ds_read_b64 v[174:175], v3 offset:2136
	ds_read_b64 v[176:177], v3 offset:4224
	ds_read_b64 v[178:179], v3 offset:4232
	ds_read_b64 v[180:181], v3 offset:4240
	ds_read_b64 v[182:183], v3 offset:4248
	ds_read_b64 v[184:185], v3 offset:6336
	ds_read_b64 v[186:187], v3 offset:6344
	ds_read_b64 v[188:189], v3 offset:6352
	ds_read_b64 v[190:191], v3 offset:6360
	s_waitcnt lgkmcnt(12)
	v_mul_f32_e32 v160, v160, v96
	v_mul_f32_e32 v161, v161, v97
	v_mul_f32_e32 v162, v162, v98
	v_mul_f32_e32 v163, v163, v99
	v_mul_f32_e32 v164, v164, v100
	v_mul_f32_e32 v165, v165, v101
	v_mul_f32_e32 v166, v166, v102
	v_mul_f32_e32 v167, v167, v103
	v_cvt_pk_bf16_f32 v192, v160, v161
	v_cvt_pk_bf16_f32 v193, v162, v163
	v_cvt_pk_bf16_f32 v194, v164, v165
	v_cvt_pk_bf16_f32 v195, v166, v167
	v_mov_b32_e32 v9, v4
	global_store_dwordx4 v9, v[192:195], s[70:71]
	s_waitcnt lgkmcnt(8)
	v_mul_f32_e32 v168, v168, v96
	v_mul_f32_e32 v169, v169, v97
	v_mul_f32_e32 v170, v170, v98
	v_mul_f32_e32 v171, v171, v99
	v_mul_f32_e32 v172, v172, v100
	v_mul_f32_e32 v173, v173, v101
	v_mul_f32_e32 v174, v174, v102
	v_mul_f32_e32 v175, v175, v103
	v_cvt_pk_bf16_f32 v196, v168, v169
	v_cvt_pk_bf16_f32 v197, v170, v171
	v_cvt_pk_bf16_f32 v198, v172, v173
	v_cvt_pk_bf16_f32 v199, v174, v175
	v_add_u32_e32 v9, 0x8000, v9
	global_store_dwordx4 v9, v[196:199], s[70:71]
	s_waitcnt lgkmcnt(4)
	v_mul_f32_e32 v176, v176, v96
	v_mul_f32_e32 v177, v177, v97
	v_mul_f32_e32 v178, v178, v98
	v_mul_f32_e32 v179, v179, v99
	v_mul_f32_e32 v180, v180, v100
	v_mul_f32_e32 v181, v181, v101
	v_mul_f32_e32 v182, v182, v102
	v_mul_f32_e32 v183, v183, v103
	v_cvt_pk_bf16_f32 v200, v176, v177
	v_cvt_pk_bf16_f32 v201, v178, v179
	v_cvt_pk_bf16_f32 v202, v180, v181
	v_cvt_pk_bf16_f32 v203, v182, v183
	v_add_u32_e32 v9, 0x8000, v9
	global_store_dwordx4 v9, v[200:203], s[70:71]
	s_waitcnt lgkmcnt(0)
	v_mul_f32_e32 v184, v184, v96
	v_mul_f32_e32 v185, v185, v97
	v_mul_f32_e32 v186, v186, v98
	v_mul_f32_e32 v187, v187, v99
	v_mul_f32_e32 v188, v188, v100
	v_mul_f32_e32 v189, v189, v101
	v_mul_f32_e32 v190, v190, v102
	v_mul_f32_e32 v191, v191, v103
	v_cvt_pk_bf16_f32 v204, v184, v185
	v_cvt_pk_bf16_f32 v205, v186, v187
	v_cvt_pk_bf16_f32 v206, v188, v189
	v_cvt_pk_bf16_f32 v207, v190, v191
	v_add_u32_e32 v9, 0x8000, v9
	global_store_dwordx4 v9, v[204:207], s[70:71]
	s_waitcnt vmcnt(0)
	s_waitcnt lgkmcnt(0)
	ds_write_b32 v2, v64 offset:0
	ds_write_b32 v2, v65 offset:264
	ds_write_b32 v2, v66 offset:528
	ds_write_b32 v2, v67 offset:792
	ds_write_b32 v2, v68 offset:32
	ds_write_b32 v2, v69 offset:296
	ds_write_b32 v2, v70 offset:560
	ds_write_b32 v2, v71 offset:824
	ds_write_b32 v2, v72 offset:64
	ds_write_b32 v2, v73 offset:328
	ds_write_b32 v2, v74 offset:592
	ds_write_b32 v2, v75 offset:856
	ds_write_b32 v2, v76 offset:96
	ds_write_b32 v2, v77 offset:360
	ds_write_b32 v2, v78 offset:624
	ds_write_b32 v2, v79 offset:888
	ds_write_b32 v2, v80 offset:128
	ds_write_b32 v2, v81 offset:392
	ds_write_b32 v2, v82 offset:656
	ds_write_b32 v2, v83 offset:920
	ds_write_b32 v2, v84 offset:160
	ds_write_b32 v2, v85 offset:424
	ds_write_b32 v2, v86 offset:688
	ds_write_b32 v2, v87 offset:952
	ds_write_b32 v2, v88 offset:192
	ds_write_b32 v2, v89 offset:456
	ds_write_b32 v2, v90 offset:720
	ds_write_b32 v2, v91 offset:984
	ds_write_b32 v2, v92 offset:224
	ds_write_b32 v2, v93 offset:488
	ds_write_b32 v2, v94 offset:752
	ds_write_b32 v2, v95 offset:1016
	s_lshr_b32 s77, s75, 5
	s_and_b32 s78, s75, 31
	s_cmp_lt_u32 s77, 2
	s_cbranch_scc0 .Lmy_p0_i2_nqk
	s_and_b32 s79, s78, 1
	s_lshl_b32 s79, s79, 7
	s_bfe_u32 s80, s78, 0x20001
	s_lshl_b32 s80, s80, 5
	s_add_i32 s79, s79, s80
	s_lshr_b32 s76, s78, 3
	s_cmp_eq_u32 s77, 1
	s_cselect_b32 s80, 12, 0
	s_add_i32 s76, s76, s80
	s_lshl_b32 s76, s76, 8
	s_add_i32 s76, s76, s79
	s_branch .Lmy_p0_i2_dd

.Lmy_p0_i2_dd:
	s_lshl_b32 s70, s76, 12
	s_lshl_b32 s71, s74, 7
	s_add_i32 s70, s70, s71
	s_add_u32 s70, s70, 0x200000
	s_add_u32 s70, s26, s70
	s_addc_u32 s71, s27, 0
	s_waitcnt lgkmcnt(0)
	ds_read_b64 v[160:161], v3 offset:0
	ds_read_b64 v[162:163], v3 offset:8
	ds_read_b64 v[164:165], v3 offset:16
	ds_read_b64 v[166:167], v3 offset:24
	ds_read_b64 v[168:169], v3 offset:2112
	ds_read_b64 v[170:171], v3 offset:2120
	ds_read_b64 v[172:173], v3 offset:2128
	ds_read_b64 v[174:175], v3 offset:2136
	ds_read_b64 v[176:177], v3 offset:4224
	ds_read_b64 v[178:179], v3 offset:4232
	ds_read_b64 v[180:181], v3 offset:4240
	ds_read_b64 v[182:183], v3 offset:4248
	ds_read_b64 v[184:185], v3 offset:6336
	ds_read_b64 v[186:187], v3 offset:6344
	ds_read_b64 v[188:189], v3 offset:6352
	ds_read_b64 v[190:191], v3 offset:6360
	s_waitcnt lgkmcnt(12)
	v_mul_f32_e32 v160, v160, v104
	v_mul_f32_e32 v161, v161, v105
	v_mul_f32_e32 v162, v162, v106
	v_mul_f32_e32 v163, v163, v107
	v_mul_f32_e32 v164, v164, v108
	v_mul_f32_e32 v165, v165, v109
	v_mul_f32_e32 v166, v166, v110
	v_mul_f32_e32 v167, v167, v111
	v_cvt_pk_bf16_f32 v192, v160, v161
	v_cvt_pk_bf16_f32 v193, v162, v163
	v_cvt_pk_bf16_f32 v194, v164, v165
	v_cvt_pk_bf16_f32 v195, v166, v167
	v_mov_b32_e32 v9, v4
	global_store_dwordx4 v9, v[192:195], s[70:71]
	s_waitcnt lgkmcnt(8)
	v_mul_f32_e32 v168, v168, v104
	v_mul_f32_e32 v169, v169, v105
	v_mul_f32_e32 v170, v170, v106
	v_mul_f32_e32 v171, v171, v107
	v_mul_f32_e32 v172, v172, v108
	v_mul_f32_e32 v173, v173, v109
	v_mul_f32_e32 v174, v174, v110
	v_mul_f32_e32 v175, v175, v111
	v_cvt_pk_bf16_f32 v196, v168, v169
	v_cvt_pk_bf16_f32 v197, v170, v171
	v_cvt_pk_bf16_f32 v198, v172, v173
	v_cvt_pk_bf16_f32 v199, v174, v175
	v_add_u32_e32 v9, 0x8000, v9
	global_store_dwordx4 v9, v[196:199], s[70:71]
	s_waitcnt lgkmcnt(4)
	v_mul_f32_e32 v176, v176, v104
	v_mul_f32_e32 v177, v177, v105
	v_mul_f32_e32 v178, v178, v106
	v_mul_f32_e32 v179, v179, v107
	v_mul_f32_e32 v180, v180, v108
	v_mul_f32_e32 v181, v181, v109
	v_mul_f32_e32 v182, v182, v110
	v_mul_f32_e32 v183, v183, v111
	v_cvt_pk_bf16_f32 v200, v176, v177
	v_cvt_pk_bf16_f32 v201, v178, v179
	v_cvt_pk_bf16_f32 v202, v180, v181
	v_cvt_pk_bf16_f32 v203, v182, v183
	v_add_u32_e32 v9, 0x8000, v9
	global_store_dwordx4 v9, v[200:203], s[70:71]
	s_waitcnt lgkmcnt(0)
	v_mul_f32_e32 v184, v184, v104
	v_mul_f32_e32 v185, v185, v105
	v_mul_f32_e32 v186, v186, v106
	v_mul_f32_e32 v187, v187, v107
	v_mul_f32_e32 v188, v188, v108
	v_mul_f32_e32 v189, v189, v109
	v_mul_f32_e32 v190, v190, v110
	v_mul_f32_e32 v191, v191, v111
	v_cvt_pk_bf16_f32 v204, v184, v185
	v_cvt_pk_bf16_f32 v205, v186, v187
	v_cvt_pk_bf16_f32 v206, v188, v189
	v_cvt_pk_bf16_f32 v207, v190, v191
	v_add_u32_e32 v9, 0x8000, v9
	global_store_dwordx4 v9, v[204:207], s[70:71]
	s_waitcnt lgkmcnt(0)
	s_branch .LBB0_241
.Lmy_p0_skip:
	s_lshl_b32 s0, s95, 14
	v_lshrrev_b32_e32 v76, 5, v209
	v_and_b32_e32 v12, 31, v208
	s_add_i32 s4, s0, 0
	v_lshlrev_b32_e32 v8, 2, v12
	v_mul_u32_u24_e32 v0, 0x84, v76
	s_waitcnt lgkmcnt(0)
	s_cmp_lg_u64 s[16:17], 0
	v_add3_u32 v77, s4, v8, v0
	v_lshlrev_b32_e32 v0, 3, v208
	v_mov_b32_e32 v1, 0
	s_cselect_b64 s[0:1], -1, 0
	v_lshrrev_b32_e32 v78, 3, v209
	v_and_b32_e32 v0, 56, v0
	s_cmp_lg_u64 s[10:11], 0
	v_mul_u32_u24_e32 v4, 0x84, v0
	v_lshlrev_b32_e32 v0, 1, v0
	v_lshlrev_b32_e32 v5, 2, v78
	v_mov_b32_e32 v9, v1
	s_cselect_b64 s[66:67], -1, 0
	s_cmp_lg_u64 s[38:39], 0
	s_mov_b32 s5, 0
	v_lshl_add_u64 v[2:3], s[52:53], 0, v[0:1]
	v_add3_u32 v79, s4, v4, v5
	v_or_b32_e32 v80, 8, v78
	v_or_b32_e32 v81, 16, v78
	v_or_b32_e32 v82, 24, v78
	v_lshl_add_u64 v[4:5], s[14:15], 0, v[8:9]
	v_lshl_add_u64 v[6:7], s[6:7], 0, v[0:1]
	v_lshl_add_u64 v[8:9], s[40:41], 0, v[8:9]
	s_cselect_b64 s[14:15], -1, 0
	v_lshl_add_u64 v[10:11], s[56:57], 0, v[0:1]
	s_lshl_b32 s63, s62, 5
	s_lshl_b32 s65, s64, 5
	s_lshl_b32 s74, s62, 7
	s_lshl_b32 s75, s64, 7
	s_movk_i32 s76, 0xca00
	v_lshlrev_b32_e32 v12, 2, v12
	s_movk_i32 s77, 0x5800
	s_movk_i32 s78, 0x7fff
	s_mov_b32 s79, 0xffff0000
	s_movk_i32 s80, 0x6000
	s_xor_b64 s[40:41], s[0:1], -1
	s_xor_b64 s[66:67], s[66:67], -1
	s_mov_b32 s81, s62
	s_branch .LBB0_26
